# idx pass 2 main loop also reuses pass-0 scores from scratch (no recompute of 16 MFMA + 240 VALU per trip)
# speedup vs baseline: 1.0255x; 1.0219x over previous
; template <int PASS>
; DI void idx_pass(const u16* kp, const bf16x8 (&qf)[8], const float (&wq)[8], int wave, int ntile, int lm, int lg, int tq, bool selall,
;                  u32 bA, u32 pfx, u32* hist, u32* maskw, u32* cand, u32* ccnt) {
;   auto ldk = [&](int t) { return *(const bf16x8*)(kp + (size_t)(t < ntile ? t : 0) * 512); };
;   int kt = wave;
;   bf16x8 ka = ldk(kt), kb = ldk(kt + 4);
; DI void idx_job(const Params& p, int b, int qg, unsigned char* smem) {
;     ...
;   const bool selall = tq + 1 <= 256;
;     ...
;   __syncthreads();
;   idx_pass<2>(kp, qf, wq, wave, ntile, lm, lg, tq, selall, binA[lm], (binA[lm] << 10) | binB[lm], hist, maskw, cand, ccnt);
.LBB0_831:
	s_or_b64 exec, exec, s[2:3]
	s_waitcnt lgkmcnt(0)
	s_barrier
	v_lshlrev_b32_e32 v160, 10, v109
	v_mov_b32_e32 v161, 0
	v_lshl_add_u64 v[160:161], v[248:249], 0, v[160:161]
	v_mov_b32_e32 v162, 0x1000
	v_mov_b32_e32 v163, 0
	v_lshl_add_u64 v[162:163], v[160:161], 0, v[162:163]
	v_cndmask_b32_e32 v160, v92, v160, vcc
	v_cndmask_b32_e32 v161, v93, v161, vcc
	v_cndmask_b32_e32 v162, v94, v162, vcc
	v_cndmask_b32_e32 v163, v95, v163, vcc
	global_load_dwordx4 v[42:45], v[160:161], off
	global_load_dwordx4 v[46:49], v[162:163], off
	v_add_u32_e32 v50, 0xc000, v136
	ds_read2_b32 v[50:51], v50 offset0:80 offset1:112
	s_movk_i32 s2, 0x100
	v_cmp_gt_u32_e64 s[40:41], s2, v87
	s_waitcnt lgkmcnt(0)
	v_lshl_or_b32 v99, v50, 10, v51
	s_and_saveexec_b64 s[2:3], vcc
	s_xor_b64 s[2:3], exec, s[2:3]
	s_cbranch_execz .LBB0_863
	s_movk_i32 s4, 0x210
	v_lshl_add_u32 v100, v88, 9, v96
	v_mad_u32_u24 v101, v88, s4, v96
	v_lshl_add_u32 v102, v109, 4, 64
	s_mov_b64 s[4:5], 0
	s_xor_b64 s[6:7], s[40:41], -1
	v_add_u32_e32 v180, 1, v99
	v_cndmask_b32_e64 v180, v180, 0, s[40:41]
	s_branch .LBB0_834

; template <int PASS, bool DIAG>
; DI void idx_tile(const bf16x8 kf, const bf16x8 (&qf)[8], const float (&wq)[8], int kt, int lm, int lg, int tq, bool selall, u32 bA, u32 pfx,
;                  u32* hist, u32* maskw, u32* cand, u32* ccnt) {
;     ...
;   u32 selbits = 0u;
; #pragma unroll
;   for (int r = 0; r < 4; ++r) {
;     const int key = kt * 16 + lg * 4 + r;
;     const bool valid = !DIAG || key <= tq;
;     const u32 bits = __float_as_uint(sc[r]);
;     const u32 u = bits ^ ((u32)((int)bits >> 31) | 0x80000000u);
;     if (PASS == 0) {
;       if (valid) { const u32 bin = u >> 22; atomicAdd(&hist[lm * 512 + (bin >> 1)], 1u << ((bin & 1) * 16)); }
;     } else if (PASS == 1) {
;       if (valid && (u >> 22) == bA) { const u32 bin = (u >> 12) & 1023u; atomicAdd(&hist[lm * 512 + (bin >> 1)], 1u << ((bin & 1) * 16)); }
;     } else {
;       const u32 pp = u >> 12;
;       if (valid && (selall || pp > pfx)) selbits |= 1u << r;
;       if (valid && !selall && pp == pfx) {
;         const u32 ix = atomicAdd(&ccnt[lm], 1u);
;         if (ix < 64u) { cand[(lm * 64 + ix) * 2] = u; cand[(lm * 64 + ix) * 2 + 1] = (u32)key; }
;       }
;     }
.LBB0_834:
	v_add_u32_e32 v103, 8, v109
	s_waitcnt vmcnt(1)
	v_mov_b64_e32 v[84:85], v[44:45]
	v_cmp_le_i32_e32 vcc, v103, v97
	v_add_u32_e32 v0, 12, v109
	v_mov_b64_e32 v[82:83], v[42:43]
	v_cmp_lt_i32_e64 s[94:95], v0, v97
	v_cndmask_b32_e32 v42, 0, v103, vcc
	v_cmp_le_i32_e32 vcc, v0, v97
	v_ashrrev_i32_e32 v43, 31, v42
	v_lshlrev_b64 v[42:43], 10, v[42:43]
	v_cndmask_b32_e32 v44, 0, v0, vcc
	v_ashrrev_i32_e32 v45, 31, v44
	v_lshlrev_b64 v[44:45], 10, v[44:45]
	v_cndmask_b32_e64 v160, v90, v248, s[94:95]
	v_cndmask_b32_e64 v161, v91, v249, s[94:95]
	v_lshl_add_u64 v[42:43], v[160:161], 0, v[42:43]
	v_lshl_add_u64 v[50:51], v[160:161], 0, v[44:45]
	global_load_dwordx4 v[42:45], v[42:43], off
	s_nop 0
	global_load_dwordx4 v[50:53], v[50:51], off
	v_add_u32_e32 v93, v98, v102
	v_ashrrev_i32_e32 v181, 31, v82
	v_bitop3_b32 v168, v181, v82, s39 bitop3:0x36
	v_lshrrev_b32_e32 v176, 12, v168
	v_ashrrev_i32_e32 v181, 31, v83
	v_bitop3_b32 v170, v181, v83, s39 bitop3:0x36
	v_lshrrev_b32_e32 v177, 12, v170
	v_ashrrev_i32_e32 v181, 31, v84
	v_bitop3_b32 v172, v181, v84, s39 bitop3:0x36
	v_lshrrev_b32_e32 v178, 12, v172
	v_ashrrev_i32_e32 v181, 31, v85
	v_bitop3_b32 v174, v181, v85, s39 bitop3:0x36
	v_lshrrev_b32_e32 v179, 12, v174
	v_cmp_eq_u32_e64 s[8:9], v176, v99
	v_cmp_eq_u32_e64 s[28:29], v177, v99
	v_cmp_eq_u32_e64 s[94:95], v178, v99
	v_cmp_eq_u32_e32 vcc, v179, v99
	s_or_b64 s[8:9], s[8:9], s[28:29]
	s_or_b64 s[28:29], vcc, s[94:95]
	s_or_b64 s[8:9], s[8:9], s[28:29]
	s_and_b64 s[8:9], s[8:9], s[6:7]
	s_cbranch_scc0 .Lidx2_nc0
	v_cmp_eq_u32_e32 vcc, v176, v99
	s_and_b64 s[28:29], s[6:7], vcc
	s_and_saveexec_b64 s[8:9], s[28:29]
	s_cbranch_execz .Lidx2_c0_0
	ds_add_rtn_u32 v181, v136, v203 offset:49408
	s_waitcnt lgkmcnt(0)
	v_cmp_gt_u32_e32 vcc, 64, v181
	s_and_b64 exec, exec, vcc
	v_subrev_u32_e32 v169, 64, v93
	v_lshl_add_u32 v181, v181, 3, v100
	ds_write_b64 v181, v[168:169] offset:41216
.Lidx2_c0_0:
	s_or_b64 exec, exec, s[8:9]
	v_cmp_eq_u32_e32 vcc, v177, v99
	s_and_b64 s[28:29], s[6:7], vcc
	s_and_saveexec_b64 s[8:9], s[28:29]
	s_cbranch_execz .Lidx2_c0_1
	ds_add_rtn_u32 v181, v136, v203 offset:49408
	s_waitcnt lgkmcnt(0)
	v_cmp_gt_u32_e32 vcc, 64, v181
	s_and_b64 exec, exec, vcc
	v_subrev_u32_e32 v171, 63, v93
	v_lshl_add_u32 v181, v181, 3, v100
	ds_write_b64 v181, v[170:171] offset:41216
.Lidx2_c0_1:
	s_or_b64 exec, exec, s[8:9]
	v_cmp_eq_u32_e32 vcc, v178, v99
	s_and_b64 s[28:29], s[6:7], vcc
	s_and_saveexec_b64 s[8:9], s[28:29]
	s_cbranch_execz .Lidx2_c0_2
	ds_add_rtn_u32 v181, v136, v203 offset:49408
	s_waitcnt lgkmcnt(0)
	v_cmp_gt_u32_e32 vcc, 64, v181
	s_and_b64 exec, exec, vcc
	v_subrev_u32_e32 v173, 62, v93
	v_lshl_add_u32 v181, v181, 3, v100
	ds_write_b64 v181, v[172:173] offset:41216
.Lidx2_c0_2:
	s_or_b64 exec, exec, s[8:9]
	v_cmp_eq_u32_e32 vcc, v179, v99
	s_and_b64 s[28:29], s[6:7], vcc
	s_and_saveexec_b64 s[8:9], s[28:29]
	s_cbranch_execz .Lidx2_c0_3
	ds_add_rtn_u32 v181, v136, v203 offset:49408
	s_waitcnt lgkmcnt(0)
	v_cmp_gt_u32_e32 vcc, 64, v181
	s_and_b64 exec, exec, vcc
	v_subrev_u32_e32 v175, 61, v93
	v_lshl_add_u32 v181, v181, 3, v100
	ds_write_b64 v181, v[174:175] offset:41216

; template <int PASS, bool DIAG>
; DI void idx_tile(const bf16x8 kf, const bf16x8 (&qf)[8], const float (&wq)[8], int kt, int lm, int lg, int tq, bool selall, u32 bA, u32 pfx,
;                  u32* hist, u32* maskw, u32* cand, u32* ccnt) {
;     ...
;       const u32 pp = u >> 12;
;       if (valid && (selall || pp > pfx)) selbits |= 1u << r;
;       if (valid && !selall && pp == pfx) {
;         const u32 ix = atomicAdd(&ccnt[lm], 1u);
;         if (ix < 64u) { cand[(lm * 64 + ix) * 2] = u; cand[(lm * 64 + ix) * 2 + 1] = (u32)key; }
;       }
;     }
;   }
;   if (PASS == 2 && selbits) {
;     const int kb = kt * 16 + lg * 4;
;     atomicOr(&maskw[lm * MW + (kb >> 5)], selbits << (kb & 31));
;   }
.Lidx2_nc0:
	v_cmp_ge_u32_e64 s[8:9], v176, v180
	v_cmp_ge_u32_e64 s[28:29], v177, v180
	v_cmp_ge_u32_e64 s[94:95], v178, v180
	v_cmp_ge_u32_e32 vcc, v179, v180
	v_cndmask_b32_e64 v0, 0, 1, s[8:9]
	v_cndmask_b32_e64 v54, 0, 2, s[28:29]
	v_cndmask_b32_e64 v55, 0, 4, s[94:95]
	v_cndmask_b32_e64 v56, 0, 8, vcc
	v_or_b32_e32 v0, v54, v0
	v_or3_b32 v0, v0, v55, v56
	v_cmp_ne_u32_e32 vcc, 0, v0
	s_and_saveexec_b64 s[8:9], vcc
	s_cbranch_execz .Lidx2_oa
	v_subrev_u32_e32 v54, 64, v102
	v_lshlrev_b32_e32 v55, 1, v109
	v_and_b32_e32 v55, -4, v55
	v_and_or_b32 v54, v54, 16, v98
	v_add_u32_e32 v55, v101, v55
	v_lshlrev_b32_e32 v0, v54, v0
	ds_or_b32 v55, v0 offset:32768
.Lidx2_oa:
	s_or_b64 exec, exec, s[8:9]
	s_waitcnt vmcnt(2)
	v_ashrrev_i32_e32 v181, 31, v46
	v_bitop3_b32 v168, v181, v46, s39 bitop3:0x36
	v_lshrrev_b32_e32 v176, 12, v168
	v_ashrrev_i32_e32 v181, 31, v47
	v_bitop3_b32 v170, v181, v47, s39 bitop3:0x36
	v_lshrrev_b32_e32 v177, 12, v170
	v_ashrrev_i32_e32 v181, 31, v48
	v_bitop3_b32 v172, v181, v48, s39 bitop3:0x36
	v_lshrrev_b32_e32 v178, 12, v172
	v_ashrrev_i32_e32 v181, 31, v49
	v_bitop3_b32 v174, v181, v49, s39 bitop3:0x36
	v_lshrrev_b32_e32 v179, 12, v174
	v_cmp_eq_u32_e64 s[8:9], v176, v99
	v_cmp_eq_u32_e64 s[28:29], v177, v99
	v_cmp_eq_u32_e64 s[94:95], v178, v99
	v_cmp_eq_u32_e32 vcc, v179, v99
	s_or_b64 s[8:9], s[8:9], s[28:29]
	s_or_b64 s[28:29], vcc, s[94:95]
	s_or_b64 s[8:9], s[8:9], s[28:29]
	s_and_b64 s[8:9], s[8:9], s[6:7]
	s_cbranch_scc0 .Lidx2_nc1
	v_cmp_eq_u32_e32 vcc, v176, v99
	s_and_b64 s[28:29], s[6:7], vcc
	s_and_saveexec_b64 s[8:9], s[28:29]
	s_cbranch_execz .Lidx2_c1_0
	ds_add_rtn_u32 v181, v136, v203 offset:49408
	s_waitcnt lgkmcnt(0)
	v_cmp_gt_u32_e32 vcc, 64, v181
	s_and_b64 exec, exec, vcc
	v_mov_b32_e32 v169, v93
	v_lshl_add_u32 v181, v181, 3, v100
	ds_write_b64 v181, v[168:169] offset:41216
.Lidx2_c1_0:
	s_or_b64 exec, exec, s[8:9]
	v_cmp_eq_u32_e32 vcc, v177, v99
	s_and_b64 s[28:29], s[6:7], vcc
	s_and_saveexec_b64 s[8:9], s[28:29]
	s_cbranch_execz .Lidx2_c1_1
	ds_add_rtn_u32 v181, v136, v203 offset:49408
	s_waitcnt lgkmcnt(0)
	v_cmp_gt_u32_e32 vcc, 64, v181
	s_and_b64 exec, exec, vcc
	v_add_u32_e32 v171, 1, v93
	v_lshl_add_u32 v181, v181, 3, v100
	ds_write_b64 v181, v[170:171] offset:41216
.Lidx2_c1_1:
	s_or_b64 exec, exec, s[8:9]
	v_cmp_eq_u32_e32 vcc, v178, v99
	s_and_b64 s[28:29], s[6:7], vcc
	s_and_saveexec_b64 s[8:9], s[28:29]
	s_cbranch_execz .Lidx2_c1_2
	ds_add_rtn_u32 v181, v136, v203 offset:49408
	s_waitcnt lgkmcnt(0)
	v_cmp_gt_u32_e32 vcc, 64, v181
	s_and_b64 exec, exec, vcc
	v_add_u32_e32 v173, 2, v93
	v_lshl_add_u32 v181, v181, 3, v100
	ds_write_b64 v181, v[172:173] offset:41216
.Lidx2_c1_2:
	s_or_b64 exec, exec, s[8:9]
	v_cmp_eq_u32_e32 vcc, v179, v99
	s_and_b64 s[28:29], s[6:7], vcc
	s_and_saveexec_b64 s[8:9], s[28:29]
	s_cbranch_execz .Lidx2_c1_3
	ds_add_rtn_u32 v181, v136, v203 offset:49408
	s_waitcnt lgkmcnt(0)
	v_cmp_gt_u32_e32 vcc, 64, v181
	s_and_b64 exec, exec, vcc
	v_add_u32_e32 v175, 3, v93
	v_lshl_add_u32 v181, v181, 3, v100
	ds_write_b64 v181, v[174:175] offset:41216

; template <int PASS, bool DIAG>
; DI void idx_tile(const bf16x8 kf, const bf16x8 (&qf)[8], const float (&wq)[8], int kt, int lm, int lg, int tq, bool selall, u32 bA, u32 pfx,
;                  u32* hist, u32* maskw, u32* cand, u32* ccnt) {
;     ...
;   if (PASS == 2 && selbits) {
;     const int kb = kt * 16 + lg * 4;
;     atomicOr(&maskw[lm * MW + (kb >> 5)], selbits << (kb & 31));
;   }
.Lidx2_nc1:
	v_cmp_ge_u32_e64 s[8:9], v176, v180
	v_cmp_ge_u32_e64 s[28:29], v177, v180
	v_cmp_ge_u32_e64 s[94:95], v178, v180
	v_cmp_ge_u32_e32 vcc, v179, v180
	v_cndmask_b32_e64 v0, 0, 1, s[8:9]
	v_cndmask_b32_e64 v54, 0, 2, s[28:29]
	v_cndmask_b32_e64 v55, 0, 4, s[94:95]
	v_cndmask_b32_e64 v56, 0, 8, vcc
	v_or_b32_e32 v0, v54, v0
	v_or3_b32 v0, v0, v55, v56
	v_cmp_ne_u32_e32 vcc, 0, v0
	s_and_saveexec_b64 s[8:9], vcc
	s_cbranch_execz .LBB0_833
	v_lshl_add_u32 v46, v109, 1, 8
	v_and_b32_e32 v46, -4, v46
	v_and_or_b32 v47, v102, 16, v98
	v_add_u32_e32 v46, v101, v46
	v_lshlrev_b32_e32 v0, v47, v0
	ds_or_b32 v46, v0 offset:32768
	s_branch .LBB0_833
